# P6 SwiGLU epilogue repack now on all four layers
# baseline (speedup 1.0000x reference)
.LBB0_3336:
	v_mov_b32_e32 v178, 0xbfb8aa3b
	v_mov_b32_e32 v179, 1.0
	s_cmp_eq_u32 s26, s48
	v_mov_b32_e32 v112, v182
	v_mov_b32_e32 v113, v183
	s_cselect_b32 s17, s71, 0x300
	s_cmp_lg_u32 s26, s47
	s_cselect_b32 s17, s17, 0x100
	v_lshl_add_u32 v114, v113, 5, s66
	s_cmp_lg_u32 s26, s46
	ds_read_b128 v[120:123], v114
	ds_read_b128 v[104:107], v114 offset:16
	ds_read_b128 v[128:131], v114 offset:256
	ds_read_b128 v[108:111], v114 offset:272
	ds_read_b128 v[190:193], v114 offset:128
	ds_read_b128 v[194:197], v114 offset:144
	ds_read_b128 v[198:201], v114 offset:384
	ds_read_b128 v[202:205], v114 offset:400
	s_cselect_b32 s17, s17, 0
	v_add_u32_e32 v176, s55, v112
	s_lshl_b32 s19, s72, 7
	v_add_u32_e32 v112, s17, v176
	s_or_b32 s19, s19, s60
	v_lshl_add_u32 v112, v112, 3, v187
	v_lshl_add_u32 v206, v113, 3, s19
	ds_read2_b64 v[156:159], v112 offset1:16
	ds_read2_b64 v[152:155], v112 offset0:32 offset1:48
	ds_read2_b64 v[148:151], v112 offset0:128 offset1:144
	ds_read2_b64 v[112:115], v112 offset0:160 offset1:176
	v_lshl_add_u32 v188, s26, 8, v176
	s_waitcnt lgkmcnt(0)
	v_mov_b32_e32 v252, v198
	v_mov_b32_e32 v253, v199
	v_ashrrev_i32_e32 v207, 31, v206
	v_pk_fma_f32 v[180:181], v[120:121], v[156:157], v[128:129] op_sel:[0,1,0]
	v_pk_fma_f32 v[208:209], v[122:123], v[156:157], v[130:131] op_sel:[0,1,0]
	v_pk_fma_f32 v[210:211], v[104:105], v[156:157], v[108:109] op_sel:[0,1,0]
	v_pk_fma_f32 v[212:213], v[106:107], v[156:157], v[110:111] op_sel:[0,1,0]
	v_pk_fma_f32 v[214:215], v[190:191], v[156:157], v[252:253] op_sel:[0,1,0]
	v_pk_fma_f32 v[216:217], v[192:193], v[156:157], v[200:201] op_sel:[0,1,0]
	v_pk_fma_f32 v[218:219], v[194:195], v[156:157], v[202:203] op_sel:[0,1,0]
	v_pk_fma_f32 v[220:221], v[196:197], v[156:157], v[204:205] op_sel:[0,1,0]
	v_pk_fma_f32 v[180:181], v[144:145], v[156:157], v[180:181] op_sel_hi:[1,0,1]
	v_pk_fma_f32 v[208:209], v[146:147], v[156:157], v[208:209] op_sel_hi:[1,0,1]
	v_pk_fma_f32 v[210:211], v[136:137], v[156:157], v[210:211] op_sel_hi:[1,0,1]
	v_pk_fma_f32 v[212:213], v[138:139], v[156:157], v[212:213] op_sel_hi:[1,0,1]
	v_pk_fma_f32 v[214:215], v[140:141], v[156:157], v[214:215] op_sel_hi:[1,0,1]
	v_pk_fma_f32 v[216:217], v[142:143], v[156:157], v[216:217] op_sel_hi:[1,0,1]
	v_pk_fma_f32 v[218:219], v[132:133], v[156:157], v[218:219] op_sel_hi:[1,0,1]
	v_pk_fma_f32 v[220:221], v[134:135], v[156:157], v[220:221] op_sel_hi:[1,0,1]
	v_pk_mul_f32 v[222:223], v[180:181], v[178:179] op_sel_hi:[1,0]
	v_pk_mul_f32 v[224:225], v[208:209], v[178:179] op_sel_hi:[1,0]
	v_pk_mul_f32 v[226:227], v[210:211], v[178:179] op_sel_hi:[1,0]
	v_pk_mul_f32 v[228:229], v[212:213], v[178:179] op_sel_hi:[1,0]
	v_exp_f32_e32 v222, v222
	v_exp_f32_e32 v223, v223
	v_exp_f32_e32 v224, v224
	v_exp_f32_e32 v225, v225
	v_exp_f32_e32 v226, v226
	v_exp_f32_e32 v227, v227
	v_exp_f32_e32 v228, v228
	v_exp_f32_e32 v229, v229
	v_pk_add_f32 v[222:223], v[222:223], v[178:179] op_sel:[0,1] op_sel_hi:[1,1]
	v_pk_add_f32 v[224:225], v[224:225], v[178:179] op_sel:[0,1] op_sel_hi:[1,1]
	v_pk_add_f32 v[226:227], v[226:227], v[178:179] op_sel:[0,1] op_sel_hi:[1,1]
	v_pk_add_f32 v[228:229], v[228:229], v[178:179] op_sel:[0,1] op_sel_hi:[1,1]
	v_rcp_f32_e32 v222, v222
	v_rcp_f32_e32 v223, v223
	v_rcp_f32_e32 v224, v224
	v_rcp_f32_e32 v225, v225
	v_rcp_f32_e32 v226, v226
	v_rcp_f32_e32 v227, v227
	v_rcp_f32_e32 v228, v228
	v_rcp_f32_e32 v229, v229
	v_pk_mul_f32 v[222:223], v[180:181], v[222:223]
	v_pk_mul_f32 v[224:225], v[208:209], v[224:225]
	v_pk_mul_f32 v[226:227], v[210:211], v[226:227]
	v_pk_mul_f32 v[228:229], v[212:213], v[228:229]
	v_pk_mul_f32 v[214:215], v[214:215], v[222:223]
	v_pk_mul_f32 v[216:217], v[216:217], v[224:225]
	v_pk_mul_f32 v[218:219], v[218:219], v[226:227]
	v_pk_mul_f32 v[220:221], v[220:221], v[228:229]
	v_cvt_pk_bf16_f32 v230, v214, v215
	v_cvt_pk_bf16_f32 v231, v216, v217
	v_cvt_pk_bf16_f32 v232, v218, v219
	v_cvt_pk_bf16_f32 v233, v220, v221
	v_mov_b64_e32 v[140:141], s[42:43]
	v_mad_i64_i32 v[198:199], s[34:35], v188, s67, v[140:141]
	v_lshlrev_b64 v[134:135], 1, v[206:207]
	v_lshl_add_u64 v[138:139], v[198:199], 0, v[134:135]
	global_store_dwordx4 v[138:139], v[230:233], off
	s_andn2_b64 vcc, exec, s[6:7]
	s_nop 1
	s_mov_b64 s[6:7], -1
	v_pk_fma_f32 v[180:181], v[120:121], v[158:159], v[128:129] op_sel:[0,1,0]
	v_pk_fma_f32 v[208:209], v[122:123], v[158:159], v[130:131] op_sel:[0,1,0]
	v_pk_fma_f32 v[210:211], v[104:105], v[158:159], v[108:109] op_sel:[0,1,0]
	v_pk_fma_f32 v[212:213], v[106:107], v[158:159], v[110:111] op_sel:[0,1,0]
	v_pk_fma_f32 v[214:215], v[190:191], v[158:159], v[252:253] op_sel:[0,1,0]
	v_pk_fma_f32 v[216:217], v[192:193], v[158:159], v[200:201] op_sel:[0,1,0]
	v_pk_fma_f32 v[218:219], v[194:195], v[158:159], v[202:203] op_sel:[0,1,0]
	v_pk_fma_f32 v[220:221], v[196:197], v[158:159], v[204:205] op_sel:[0,1,0]
	v_pk_fma_f32 v[180:181], v[124:125], v[158:159], v[180:181] op_sel_hi:[1,0,1]
	v_pk_fma_f32 v[208:209], v[126:127], v[158:159], v[208:209] op_sel_hi:[1,0,1]
	v_pk_fma_f32 v[210:211], v[100:101], v[158:159], v[210:211] op_sel_hi:[1,0,1]
	v_pk_fma_f32 v[212:213], v[102:103], v[158:159], v[212:213] op_sel_hi:[1,0,1]
	v_pk_fma_f32 v[214:215], v[116:117], v[158:159], v[214:215] op_sel_hi:[1,0,1]
	v_pk_fma_f32 v[216:217], v[118:119], v[158:159], v[216:217] op_sel_hi:[1,0,1]
	v_pk_fma_f32 v[218:219], v[96:97], v[158:159], v[218:219] op_sel_hi:[1,0,1]
	v_pk_fma_f32 v[220:221], v[98:99], v[158:159], v[220:221] op_sel_hi:[1,0,1]
	v_pk_mul_f32 v[222:223], v[180:181], v[178:179] op_sel_hi:[1,0]
	v_pk_mul_f32 v[224:225], v[208:209], v[178:179] op_sel_hi:[1,0]
	v_pk_mul_f32 v[226:227], v[210:211], v[178:179] op_sel_hi:[1,0]
	v_pk_mul_f32 v[228:229], v[212:213], v[178:179] op_sel_hi:[1,0]
	v_exp_f32_e32 v222, v222
	v_exp_f32_e32 v223, v223
	v_exp_f32_e32 v224, v224
	v_exp_f32_e32 v225, v225
	v_exp_f32_e32 v226, v226
	v_exp_f32_e32 v227, v227
	v_exp_f32_e32 v228, v228
	v_exp_f32_e32 v229, v229
	v_pk_add_f32 v[222:223], v[222:223], v[178:179] op_sel:[0,1] op_sel_hi:[1,1]
	v_pk_add_f32 v[224:225], v[224:225], v[178:179] op_sel:[0,1] op_sel_hi:[1,1]
	v_pk_add_f32 v[226:227], v[226:227], v[178:179] op_sel:[0,1] op_sel_hi:[1,1]
	v_pk_add_f32 v[228:229], v[228:229], v[178:179] op_sel:[0,1] op_sel_hi:[1,1]
	v_rcp_f32_e32 v222, v222
	v_rcp_f32_e32 v223, v223
	v_rcp_f32_e32 v224, v224
	v_rcp_f32_e32 v225, v225
	v_rcp_f32_e32 v226, v226
	v_rcp_f32_e32 v227, v227
	v_rcp_f32_e32 v228, v228
	v_rcp_f32_e32 v229, v229
	v_pk_mul_f32 v[222:223], v[180:181], v[222:223]
	v_pk_mul_f32 v[224:225], v[208:209], v[224:225]
	v_pk_mul_f32 v[226:227], v[210:211], v[226:227]
	v_pk_mul_f32 v[228:229], v[212:213], v[228:229]
	v_pk_mul_f32 v[214:215], v[214:215], v[222:223]
	v_pk_mul_f32 v[216:217], v[216:217], v[224:225]
	v_pk_mul_f32 v[218:219], v[218:219], v[226:227]
	v_pk_mul_f32 v[220:221], v[220:221], v[228:229]
	v_cvt_pk_bf16_f32 v234, v214, v215
	v_cvt_pk_bf16_f32 v235, v216, v217
	v_cvt_pk_bf16_f32 v236, v218, v219
	v_cvt_pk_bf16_f32 v237, v220, v221
	v_add_u32_e32 v125, 16, v188
	v_mad_i64_i32 v[124:125], s[34:35], v125, s67, v[140:141]
	v_lshl_add_u64 v[100:101], v[124:125], 0, v[134:135]
	global_store_dwordx4 v[100:101], v[234:237], off
	v_pk_fma_f32 v[180:181], v[120:121], v[152:153], v[128:129] op_sel:[0,1,0]
	v_pk_fma_f32 v[208:209], v[122:123], v[152:153], v[130:131] op_sel:[0,1,0]
	v_pk_fma_f32 v[210:211], v[104:105], v[152:153], v[108:109] op_sel:[0,1,0]
	v_pk_fma_f32 v[212:213], v[106:107], v[152:153], v[110:111] op_sel:[0,1,0]
	v_pk_fma_f32 v[214:215], v[190:191], v[152:153], v[252:253] op_sel:[0,1,0]
	v_pk_fma_f32 v[216:217], v[192:193], v[152:153], v[200:201] op_sel:[0,1,0]
	v_pk_fma_f32 v[218:219], v[194:195], v[152:153], v[202:203] op_sel:[0,1,0]
	v_pk_fma_f32 v[220:221], v[196:197], v[152:153], v[204:205] op_sel:[0,1,0]
	v_pk_fma_f32 v[180:181], v[92:93], v[152:153], v[180:181] op_sel_hi:[1,0,1]
	v_pk_fma_f32 v[208:209], v[94:95], v[152:153], v[208:209] op_sel_hi:[1,0,1]
	v_pk_fma_f32 v[210:211], v[84:85], v[152:153], v[210:211] op_sel_hi:[1,0,1]
	v_pk_fma_f32 v[212:213], v[86:87], v[152:153], v[212:213] op_sel_hi:[1,0,1]
	v_pk_fma_f32 v[214:215], v[88:89], v[152:153], v[214:215] op_sel_hi:[1,0,1]
	v_pk_fma_f32 v[216:217], v[90:91], v[152:153], v[216:217] op_sel_hi:[1,0,1]
	v_pk_fma_f32 v[218:219], v[80:81], v[152:153], v[218:219] op_sel_hi:[1,0,1]
	v_pk_fma_f32 v[220:221], v[82:83], v[152:153], v[220:221] op_sel_hi:[1,0,1]
	v_pk_mul_f32 v[222:223], v[180:181], v[178:179] op_sel_hi:[1,0]
	v_pk_mul_f32 v[224:225], v[208:209], v[178:179] op_sel_hi:[1,0]
	v_pk_mul_f32 v[226:227], v[210:211], v[178:179] op_sel_hi:[1,0]
	v_pk_mul_f32 v[228:229], v[212:213], v[178:179] op_sel_hi:[1,0]
	v_exp_f32_e32 v222, v222
	v_exp_f32_e32 v223, v223
	v_exp_f32_e32 v224, v224
	v_exp_f32_e32 v225, v225
	v_exp_f32_e32 v226, v226
	v_exp_f32_e32 v227, v227
	v_exp_f32_e32 v228, v228
	v_exp_f32_e32 v229, v229
	v_pk_add_f32 v[222:223], v[222:223], v[178:179] op_sel:[0,1] op_sel_hi:[1,1]
	v_pk_add_f32 v[224:225], v[224:225], v[178:179] op_sel:[0,1] op_sel_hi:[1,1]
	v_pk_add_f32 v[226:227], v[226:227], v[178:179] op_sel:[0,1] op_sel_hi:[1,1]
	v_pk_add_f32 v[228:229], v[228:229], v[178:179] op_sel:[0,1] op_sel_hi:[1,1]
	v_rcp_f32_e32 v222, v222
	v_rcp_f32_e32 v223, v223
	v_rcp_f32_e32 v224, v224
	v_rcp_f32_e32 v225, v225
	v_rcp_f32_e32 v226, v226
	v_rcp_f32_e32 v227, v227
	v_rcp_f32_e32 v228, v228
	v_rcp_f32_e32 v229, v229
	v_pk_mul_f32 v[222:223], v[180:181], v[222:223]
	v_pk_mul_f32 v[224:225], v[208:209], v[224:225]
	v_pk_mul_f32 v[226:227], v[210:211], v[226:227]
	v_pk_mul_f32 v[228:229], v[212:213], v[228:229]
	v_pk_mul_f32 v[214:215], v[214:215], v[222:223]
	v_pk_mul_f32 v[216:217], v[216:217], v[224:225]
	v_pk_mul_f32 v[218:219], v[218:219], v[226:227]
	v_pk_mul_f32 v[220:221], v[220:221], v[228:229]
	v_cvt_pk_bf16_f32 v238, v214, v215
	v_cvt_pk_bf16_f32 v239, v216, v217
	v_cvt_pk_bf16_f32 v240, v218, v219
	v_cvt_pk_bf16_f32 v241, v220, v221
	v_add_u32_e32 v93, 32, v188
	v_mad_i64_i32 v[92:93], s[34:35], v93, s67, v[140:141]
	v_lshl_add_u64 v[84:85], v[92:93], 0, v[134:135]
	global_store_dwordx4 v[84:85], v[238:241], off
	v_pk_fma_f32 v[180:181], v[120:121], v[154:155], v[128:129] op_sel:[0,1,0]
	v_pk_fma_f32 v[208:209], v[122:123], v[154:155], v[130:131] op_sel:[0,1,0]
	v_pk_fma_f32 v[210:211], v[104:105], v[154:155], v[108:109] op_sel:[0,1,0]
	v_pk_fma_f32 v[212:213], v[106:107], v[154:155], v[110:111] op_sel:[0,1,0]
	v_pk_fma_f32 v[214:215], v[190:191], v[154:155], v[252:253] op_sel:[0,1,0]
	v_pk_fma_f32 v[216:217], v[192:193], v[154:155], v[200:201] op_sel:[0,1,0]
	v_pk_fma_f32 v[218:219], v[194:195], v[154:155], v[202:203] op_sel:[0,1,0]
	v_pk_fma_f32 v[220:221], v[196:197], v[154:155], v[204:205] op_sel:[0,1,0]
	v_pk_fma_f32 v[180:181], v[76:77], v[154:155], v[180:181] op_sel_hi:[1,0,1]
	v_pk_fma_f32 v[208:209], v[78:79], v[154:155], v[208:209] op_sel_hi:[1,0,1]
	v_pk_fma_f32 v[210:211], v[68:69], v[154:155], v[210:211] op_sel_hi:[1,0,1]
	v_pk_fma_f32 v[212:213], v[70:71], v[154:155], v[212:213] op_sel_hi:[1,0,1]
	v_pk_fma_f32 v[214:215], v[72:73], v[154:155], v[214:215] op_sel_hi:[1,0,1]
	v_pk_fma_f32 v[216:217], v[74:75], v[154:155], v[216:217] op_sel_hi:[1,0,1]
	v_pk_fma_f32 v[218:219], v[64:65], v[154:155], v[218:219] op_sel_hi:[1,0,1]
	v_pk_fma_f32 v[220:221], v[66:67], v[154:155], v[220:221] op_sel_hi:[1,0,1]
	v_pk_mul_f32 v[222:223], v[180:181], v[178:179] op_sel_hi:[1,0]
	v_pk_mul_f32 v[224:225], v[208:209], v[178:179] op_sel_hi:[1,0]
	v_pk_mul_f32 v[226:227], v[210:211], v[178:179] op_sel_hi:[1,0]
	v_pk_mul_f32 v[228:229], v[212:213], v[178:179] op_sel_hi:[1,0]
	v_exp_f32_e32 v222, v222
	v_exp_f32_e32 v223, v223
	v_exp_f32_e32 v224, v224
	v_exp_f32_e32 v225, v225
	v_exp_f32_e32 v226, v226
	v_exp_f32_e32 v227, v227
	v_exp_f32_e32 v228, v228
	v_exp_f32_e32 v229, v229
	v_pk_add_f32 v[222:223], v[222:223], v[178:179] op_sel:[0,1] op_sel_hi:[1,1]
	v_pk_add_f32 v[224:225], v[224:225], v[178:179] op_sel:[0,1] op_sel_hi:[1,1]
	v_pk_add_f32 v[226:227], v[226:227], v[178:179] op_sel:[0,1] op_sel_hi:[1,1]
	v_pk_add_f32 v[228:229], v[228:229], v[178:179] op_sel:[0,1] op_sel_hi:[1,1]
	v_rcp_f32_e32 v222, v222
	v_rcp_f32_e32 v223, v223
	v_rcp_f32_e32 v224, v224
	v_rcp_f32_e32 v225, v225
	v_rcp_f32_e32 v226, v226
	v_rcp_f32_e32 v227, v227
	v_rcp_f32_e32 v228, v228
	v_rcp_f32_e32 v229, v229
	v_pk_mul_f32 v[222:223], v[180:181], v[222:223]
	v_pk_mul_f32 v[224:225], v[208:209], v[224:225]
	v_pk_mul_f32 v[226:227], v[210:211], v[226:227]
	v_pk_mul_f32 v[228:229], v[212:213], v[228:229]
	v_pk_mul_f32 v[214:215], v[214:215], v[222:223]
	v_pk_mul_f32 v[216:217], v[216:217], v[224:225]
	v_pk_mul_f32 v[218:219], v[218:219], v[226:227]
	v_pk_mul_f32 v[220:221], v[220:221], v[228:229]
	v_cvt_pk_bf16_f32 v242, v214, v215
	v_cvt_pk_bf16_f32 v243, v216, v217
	v_cvt_pk_bf16_f32 v244, v218, v219
	v_cvt_pk_bf16_f32 v245, v220, v221
	v_add_u32_e32 v77, 48, v188
	v_mad_i64_i32 v[76:77], s[34:35], v77, s67, v[140:141]
	v_lshl_add_u64 v[68:69], v[76:77], 0, v[134:135]
	global_store_dwordx4 v[68:69], v[242:245], off
	v_pk_fma_f32 v[180:181], v[120:121], v[148:149], v[128:129] op_sel:[0,1,0]
	v_pk_fma_f32 v[208:209], v[122:123], v[148:149], v[130:131] op_sel:[0,1,0]
	v_pk_fma_f32 v[210:211], v[104:105], v[148:149], v[108:109] op_sel:[0,1,0]
	v_pk_fma_f32 v[212:213], v[106:107], v[148:149], v[110:111] op_sel:[0,1,0]
	v_pk_fma_f32 v[214:215], v[190:191], v[148:149], v[252:253] op_sel:[0,1,0]
	v_pk_fma_f32 v[216:217], v[192:193], v[148:149], v[200:201] op_sel:[0,1,0]
	v_pk_fma_f32 v[218:219], v[194:195], v[148:149], v[202:203] op_sel:[0,1,0]
	v_pk_fma_f32 v[220:221], v[196:197], v[148:149], v[204:205] op_sel:[0,1,0]
	v_pk_fma_f32 v[180:181], v[60:61], v[148:149], v[180:181] op_sel_hi:[1,0,1]
	v_pk_fma_f32 v[208:209], v[62:63], v[148:149], v[208:209] op_sel_hi:[1,0,1]
	v_pk_fma_f32 v[210:211], v[52:53], v[148:149], v[210:211] op_sel_hi:[1,0,1]
	v_pk_fma_f32 v[212:213], v[54:55], v[148:149], v[212:213] op_sel_hi:[1,0,1]
	v_pk_fma_f32 v[214:215], v[56:57], v[148:149], v[214:215] op_sel_hi:[1,0,1]
	v_pk_fma_f32 v[216:217], v[58:59], v[148:149], v[216:217] op_sel_hi:[1,0,1]
	v_pk_fma_f32 v[218:219], v[48:49], v[148:149], v[218:219] op_sel_hi:[1,0,1]
	v_pk_fma_f32 v[220:221], v[50:51], v[148:149], v[220:221] op_sel_hi:[1,0,1]
	v_pk_mul_f32 v[222:223], v[180:181], v[178:179] op_sel_hi:[1,0]
	v_pk_mul_f32 v[224:225], v[208:209], v[178:179] op_sel_hi:[1,0]
	v_pk_mul_f32 v[226:227], v[210:211], v[178:179] op_sel_hi:[1,0]
	v_pk_mul_f32 v[228:229], v[212:213], v[178:179] op_sel_hi:[1,0]
	v_exp_f32_e32 v222, v222
	v_exp_f32_e32 v223, v223
	v_exp_f32_e32 v224, v224
	v_exp_f32_e32 v225, v225
	v_exp_f32_e32 v226, v226
	v_exp_f32_e32 v227, v227
	v_exp_f32_e32 v228, v228
	v_exp_f32_e32 v229, v229
	v_pk_add_f32 v[222:223], v[222:223], v[178:179] op_sel:[0,1] op_sel_hi:[1,1]
	v_pk_add_f32 v[224:225], v[224:225], v[178:179] op_sel:[0,1] op_sel_hi:[1,1]
	v_pk_add_f32 v[226:227], v[226:227], v[178:179] op_sel:[0,1] op_sel_hi:[1,1]
	v_pk_add_f32 v[228:229], v[228:229], v[178:179] op_sel:[0,1] op_sel_hi:[1,1]
	v_rcp_f32_e32 v222, v222
	v_rcp_f32_e32 v223, v223
	v_rcp_f32_e32 v224, v224
	v_rcp_f32_e32 v225, v225
	v_rcp_f32_e32 v226, v226
	v_rcp_f32_e32 v227, v227
	v_rcp_f32_e32 v228, v228
	v_rcp_f32_e32 v229, v229
	v_pk_mul_f32 v[222:223], v[180:181], v[222:223]
	v_pk_mul_f32 v[224:225], v[208:209], v[224:225]
	v_pk_mul_f32 v[226:227], v[210:211], v[226:227]
	v_pk_mul_f32 v[228:229], v[212:213], v[228:229]
	v_pk_mul_f32 v[214:215], v[214:215], v[222:223]
	v_pk_mul_f32 v[216:217], v[216:217], v[224:225]
	v_pk_mul_f32 v[218:219], v[218:219], v[226:227]
	v_pk_mul_f32 v[220:221], v[220:221], v[228:229]
	v_cvt_pk_bf16_f32 v246, v214, v215
	v_cvt_pk_bf16_f32 v247, v216, v217
	v_cvt_pk_bf16_f32 v248, v218, v219
	v_cvt_pk_bf16_f32 v249, v220, v221
	v_add_u32_e32 v61, 0x80, v188
	v_mad_i64_i32 v[60:61], s[34:35], v61, s67, v[140:141]
	v_lshl_add_u64 v[52:53], v[60:61], 0, v[134:135]
	global_store_dwordx4 v[52:53], v[246:249], off
	v_pk_fma_f32 v[180:181], v[120:121], v[150:151], v[128:129] op_sel:[0,1,0]
	v_pk_fma_f32 v[208:209], v[122:123], v[150:151], v[130:131] op_sel:[0,1,0]
	v_pk_fma_f32 v[210:211], v[104:105], v[150:151], v[108:109] op_sel:[0,1,0]
	v_pk_fma_f32 v[212:213], v[106:107], v[150:151], v[110:111] op_sel:[0,1,0]
	v_pk_fma_f32 v[214:215], v[190:191], v[150:151], v[252:253] op_sel:[0,1,0]
	v_pk_fma_f32 v[216:217], v[192:193], v[150:151], v[200:201] op_sel:[0,1,0]
	v_pk_fma_f32 v[218:219], v[194:195], v[150:151], v[202:203] op_sel:[0,1,0]
	v_pk_fma_f32 v[220:221], v[196:197], v[150:151], v[204:205] op_sel:[0,1,0]
	v_pk_fma_f32 v[180:181], v[44:45], v[150:151], v[180:181] op_sel_hi:[1,0,1]
	v_pk_fma_f32 v[208:209], v[46:47], v[150:151], v[208:209] op_sel_hi:[1,0,1]
	v_pk_fma_f32 v[210:211], v[36:37], v[150:151], v[210:211] op_sel_hi:[1,0,1]
	v_pk_fma_f32 v[212:213], v[38:39], v[150:151], v[212:213] op_sel_hi:[1,0,1]
	v_pk_fma_f32 v[214:215], v[40:41], v[150:151], v[214:215] op_sel_hi:[1,0,1]
	v_pk_fma_f32 v[216:217], v[42:43], v[150:151], v[216:217] op_sel_hi:[1,0,1]
	v_pk_fma_f32 v[218:219], v[32:33], v[150:151], v[218:219] op_sel_hi:[1,0,1]
	v_pk_fma_f32 v[220:221], v[34:35], v[150:151], v[220:221] op_sel_hi:[1,0,1]
	v_pk_mul_f32 v[222:223], v[180:181], v[178:179] op_sel_hi:[1,0]
	v_pk_mul_f32 v[224:225], v[208:209], v[178:179] op_sel_hi:[1,0]
	v_pk_mul_f32 v[226:227], v[210:211], v[178:179] op_sel_hi:[1,0]
	v_pk_mul_f32 v[228:229], v[212:213], v[178:179] op_sel_hi:[1,0]
	v_exp_f32_e32 v222, v222
	v_exp_f32_e32 v223, v223
	v_exp_f32_e32 v224, v224
	v_exp_f32_e32 v225, v225
	v_exp_f32_e32 v226, v226
	v_exp_f32_e32 v227, v227
	v_exp_f32_e32 v228, v228
	v_exp_f32_e32 v229, v229
	v_pk_add_f32 v[222:223], v[222:223], v[178:179] op_sel:[0,1] op_sel_hi:[1,1]
	v_pk_add_f32 v[224:225], v[224:225], v[178:179] op_sel:[0,1] op_sel_hi:[1,1]
	v_pk_add_f32 v[226:227], v[226:227], v[178:179] op_sel:[0,1] op_sel_hi:[1,1]
	v_pk_add_f32 v[228:229], v[228:229], v[178:179] op_sel:[0,1] op_sel_hi:[1,1]
	v_rcp_f32_e32 v222, v222
	v_rcp_f32_e32 v223, v223
	v_rcp_f32_e32 v224, v224
	v_rcp_f32_e32 v225, v225
	v_rcp_f32_e32 v226, v226
	v_rcp_f32_e32 v227, v227
	v_rcp_f32_e32 v228, v228
	v_rcp_f32_e32 v229, v229
	v_pk_mul_f32 v[222:223], v[180:181], v[222:223]
	v_pk_mul_f32 v[224:225], v[208:209], v[224:225]
	v_pk_mul_f32 v[226:227], v[210:211], v[226:227]
	v_pk_mul_f32 v[228:229], v[212:213], v[228:229]
	v_pk_mul_f32 v[214:215], v[214:215], v[222:223]
	v_pk_mul_f32 v[216:217], v[216:217], v[224:225]
	v_pk_mul_f32 v[218:219], v[218:219], v[226:227]
	v_pk_mul_f32 v[220:221], v[220:221], v[228:229]
	v_cvt_pk_bf16_f32 v230, v214, v215
	v_cvt_pk_bf16_f32 v231, v216, v217
	v_cvt_pk_bf16_f32 v232, v218, v219
	v_cvt_pk_bf16_f32 v233, v220, v221
	v_add_u32_e32 v45, 0x90, v188
	v_mad_i64_i32 v[44:45], s[34:35], v45, s67, v[140:141]
	v_lshl_add_u64 v[36:37], v[44:45], 0, v[134:135]
	global_store_dwordx4 v[36:37], v[230:233], off
	v_pk_fma_f32 v[180:181], v[120:121], v[112:113], v[128:129] op_sel:[0,1,0]
	v_pk_fma_f32 v[208:209], v[122:123], v[112:113], v[130:131] op_sel:[0,1,0]
	v_pk_fma_f32 v[210:211], v[104:105], v[112:113], v[108:109] op_sel:[0,1,0]
	v_pk_fma_f32 v[212:213], v[106:107], v[112:113], v[110:111] op_sel:[0,1,0]
	v_pk_fma_f32 v[214:215], v[190:191], v[112:113], v[252:253] op_sel:[0,1,0]
	v_pk_fma_f32 v[216:217], v[192:193], v[112:113], v[200:201] op_sel:[0,1,0]
	v_pk_fma_f32 v[218:219], v[194:195], v[112:113], v[202:203] op_sel:[0,1,0]
	v_pk_fma_f32 v[220:221], v[196:197], v[112:113], v[204:205] op_sel:[0,1,0]
	v_pk_fma_f32 v[180:181], v[28:29], v[112:113], v[180:181] op_sel_hi:[1,0,1]
	v_pk_fma_f32 v[208:209], v[30:31], v[112:113], v[208:209] op_sel_hi:[1,0,1]
	v_pk_fma_f32 v[210:211], v[20:21], v[112:113], v[210:211] op_sel_hi:[1,0,1]
	v_pk_fma_f32 v[212:213], v[22:23], v[112:113], v[212:213] op_sel_hi:[1,0,1]
	v_pk_fma_f32 v[214:215], v[24:25], v[112:113], v[214:215] op_sel_hi:[1,0,1]
	v_pk_fma_f32 v[216:217], v[26:27], v[112:113], v[216:217] op_sel_hi:[1,0,1]
	v_pk_fma_f32 v[218:219], v[16:17], v[112:113], v[218:219] op_sel_hi:[1,0,1]
	v_pk_fma_f32 v[220:221], v[18:19], v[112:113], v[220:221] op_sel_hi:[1,0,1]
	v_pk_mul_f32 v[222:223], v[180:181], v[178:179] op_sel_hi:[1,0]
	v_pk_mul_f32 v[224:225], v[208:209], v[178:179] op_sel_hi:[1,0]
	v_pk_mul_f32 v[226:227], v[210:211], v[178:179] op_sel_hi:[1,0]
	v_pk_mul_f32 v[228:229], v[212:213], v[178:179] op_sel_hi:[1,0]
	v_exp_f32_e32 v222, v222
	v_exp_f32_e32 v223, v223
	v_exp_f32_e32 v224, v224
	v_exp_f32_e32 v225, v225
	v_exp_f32_e32 v226, v226
	v_exp_f32_e32 v227, v227
	v_exp_f32_e32 v228, v228
	v_exp_f32_e32 v229, v229
	v_pk_add_f32 v[222:223], v[222:223], v[178:179] op_sel:[0,1] op_sel_hi:[1,1]
	v_pk_add_f32 v[224:225], v[224:225], v[178:179] op_sel:[0,1] op_sel_hi:[1,1]
	v_pk_add_f32 v[226:227], v[226:227], v[178:179] op_sel:[0,1] op_sel_hi:[1,1]
	v_pk_add_f32 v[228:229], v[228:229], v[178:179] op_sel:[0,1] op_sel_hi:[1,1]
	v_rcp_f32_e32 v222, v222
	v_rcp_f32_e32 v223, v223
	v_rcp_f32_e32 v224, v224
	v_rcp_f32_e32 v225, v225
	v_rcp_f32_e32 v226, v226
	v_rcp_f32_e32 v227, v227
	v_rcp_f32_e32 v228, v228
	v_rcp_f32_e32 v229, v229
	v_pk_mul_f32 v[222:223], v[180:181], v[222:223]
	v_pk_mul_f32 v[224:225], v[208:209], v[224:225]
	v_pk_mul_f32 v[226:227], v[210:211], v[226:227]
	v_pk_mul_f32 v[228:229], v[212:213], v[228:229]
	v_pk_mul_f32 v[214:215], v[214:215], v[222:223]
	v_pk_mul_f32 v[216:217], v[216:217], v[224:225]
	v_pk_mul_f32 v[218:219], v[218:219], v[226:227]
	v_pk_mul_f32 v[220:221], v[220:221], v[228:229]
	v_cvt_pk_bf16_f32 v234, v214, v215
	v_cvt_pk_bf16_f32 v235, v216, v217
	v_cvt_pk_bf16_f32 v236, v218, v219
	v_cvt_pk_bf16_f32 v237, v220, v221
	v_add_u32_e32 v29, 0xa0, v188
	v_mad_i64_i32 v[28:29], s[34:35], v29, s67, v[140:141]
	v_lshl_add_u64 v[20:21], v[28:29], 0, v[134:135]
	global_store_dwordx4 v[20:21], v[234:237], off
	v_pk_fma_f32 v[180:181], v[120:121], v[114:115], v[128:129] op_sel:[0,1,0]
	v_pk_fma_f32 v[208:209], v[122:123], v[114:115], v[130:131] op_sel:[0,1,0]
	v_pk_fma_f32 v[210:211], v[104:105], v[114:115], v[108:109] op_sel:[0,1,0]
	v_pk_fma_f32 v[212:213], v[106:107], v[114:115], v[110:111] op_sel:[0,1,0]
	v_pk_fma_f32 v[214:215], v[190:191], v[114:115], v[252:253] op_sel:[0,1,0]
	v_pk_fma_f32 v[216:217], v[192:193], v[114:115], v[200:201] op_sel:[0,1,0]
	v_pk_fma_f32 v[218:219], v[194:195], v[114:115], v[202:203] op_sel:[0,1,0]
	v_pk_fma_f32 v[220:221], v[196:197], v[114:115], v[204:205] op_sel:[0,1,0]
	v_pk_fma_f32 v[180:181], v[12:13], v[114:115], v[180:181] op_sel_hi:[1,0,1]
	v_pk_fma_f32 v[208:209], v[14:15], v[114:115], v[208:209] op_sel_hi:[1,0,1]
	v_pk_fma_f32 v[210:211], v[4:5], v[114:115], v[210:211] op_sel_hi:[1,0,1]
	v_pk_fma_f32 v[212:213], v[6:7], v[114:115], v[212:213] op_sel_hi:[1,0,1]
	v_pk_fma_f32 v[214:215], v[8:9], v[114:115], v[214:215] op_sel_hi:[1,0,1]
	v_pk_fma_f32 v[216:217], v[10:11], v[114:115], v[216:217] op_sel_hi:[1,0,1]
	v_pk_fma_f32 v[218:219], v[0:1], v[114:115], v[218:219] op_sel_hi:[1,0,1]
	v_pk_fma_f32 v[220:221], v[2:3], v[114:115], v[220:221] op_sel_hi:[1,0,1]
	v_pk_mul_f32 v[222:223], v[180:181], v[178:179] op_sel_hi:[1,0]
	v_pk_mul_f32 v[224:225], v[208:209], v[178:179] op_sel_hi:[1,0]
	v_pk_mul_f32 v[226:227], v[210:211], v[178:179] op_sel_hi:[1,0]
	v_pk_mul_f32 v[228:229], v[212:213], v[178:179] op_sel_hi:[1,0]
	v_exp_f32_e32 v222, v222
	v_exp_f32_e32 v223, v223
	v_exp_f32_e32 v224, v224
	v_exp_f32_e32 v225, v225
	v_exp_f32_e32 v226, v226
	v_exp_f32_e32 v227, v227
	v_exp_f32_e32 v228, v228
	v_exp_f32_e32 v229, v229
	v_pk_add_f32 v[222:223], v[222:223], v[178:179] op_sel:[0,1] op_sel_hi:[1,1]
	v_pk_add_f32 v[224:225], v[224:225], v[178:179] op_sel:[0,1] op_sel_hi:[1,1]
	v_pk_add_f32 v[226:227], v[226:227], v[178:179] op_sel:[0,1] op_sel_hi:[1,1]
	v_pk_add_f32 v[228:229], v[228:229], v[178:179] op_sel:[0,1] op_sel_hi:[1,1]
	v_rcp_f32_e32 v222, v222
	v_rcp_f32_e32 v223, v223
	v_rcp_f32_e32 v224, v224
	v_rcp_f32_e32 v225, v225
	v_rcp_f32_e32 v226, v226
	v_rcp_f32_e32 v227, v227
	v_rcp_f32_e32 v228, v228
	v_rcp_f32_e32 v229, v229
	v_pk_mul_f32 v[222:223], v[180:181], v[222:223]
	v_pk_mul_f32 v[224:225], v[208:209], v[224:225]
	v_pk_mul_f32 v[226:227], v[210:211], v[226:227]
	v_pk_mul_f32 v[228:229], v[212:213], v[228:229]
	v_pk_mul_f32 v[214:215], v[214:215], v[222:223]
	v_pk_mul_f32 v[216:217], v[216:217], v[224:225]
	v_pk_mul_f32 v[218:219], v[218:219], v[226:227]
	v_pk_mul_f32 v[220:221], v[220:221], v[228:229]
	v_cvt_pk_bf16_f32 v238, v214, v215
	v_cvt_pk_bf16_f32 v239, v216, v217
	v_cvt_pk_bf16_f32 v240, v218, v219
	v_cvt_pk_bf16_f32 v241, v220, v221
	v_add_u32_e32 v13, 0xb0, v188
	v_mad_i64_i32 v[12:13], s[34:35], v13, s67, v[140:141]
	v_lshl_add_u64 v[4:5], v[12:13], 0, v[134:135]
	global_store_dwordx4 v[4:5], v[238:241], off
	s_mov_b32 s99, 1
	s_cbranch_vccnz .LBB0_3327
	s_andn2_b64 vcc, exec, s[0:1]
	s_cbranch_vccnz .LBB0_3326
	s_barrier
	s_branch .LBB0_3326
